# v26 + GEMM mainloop: deleted the redundant s_setprio 0 / s_setprio 1 pair in the middle of each 32-MFMA block
# speedup vs baseline: 1.0040x; 1.0021x over previous
; #define PG8_STAGE(bufoff, gbase, voff) do { _Pragma("unroll") for (int _i = 0; _i < 2; ++_i) \
;         __builtin_amdgcn_global_load_lds((const unsigned*)((const char*)(gbase) + (voff)[_i]), (PG8_LAS unsigned*)(lds + (bufoff) + ldsw + _i * 8192), 16, 0, 0); } while (0)
; #define PG8_LDA(dst, b, h) do { _Pragma("unroll") for (int m = 0; m < 4; ++m) _Pragma("unroll") for (int k = 0; k < 2; ++k) dst[m][k] = *(const PG8_LAS bf16x8*)(lds + PG8_SA(b, h) + aoff + m * 2048 + k * 1024); } while (0)
; #define PG8_LDB(dst, b, h) do { _Pragma("unroll") for (int n = 0; n < 2; ++n) _Pragma("unroll") for (int k = 0; k < 2; ++k) dst[n][k] = *(const PG8_LAS bf16x8*)(lds + PG8_SB(b, h) + boff + n * 2048 + k * 1024); } while (0)
; #define PG8_MMA(ai, bj, At, Bt) do { __builtin_amdgcn_s_setprio(1); _Pragma("unroll") for (int m = 0; m < 4; ++m) _Pragma("unroll") for (int n = 0; n < 2; ++n) _Pragma("unroll") for (int k = 0; k < 2; ++k) \
;         acc[ai][bj][m][n] = __builtin_amdgcn_mfma_f32_16x16x32_bf16(Bt[n][k], At[m][k], acc[ai][bj][m][n], 0, 0, 0); __builtin_amdgcn_s_setprio(0); } while (0)
; #define PG8_WAIT_V(n) asm volatile("s_waitcnt vmcnt(" #n ")" ::: "memory")
; #define PG8_BAR __builtin_amdgcn_s_barrier()
; template <class Epi, class Sched, bool ALIGN_EPI = false, bool SP2 = false>
; __device__ __forceinline__ void gemm_phase(PG8_LAS unsigned char* lds, const Gemm g, const Sched& S, const Epi& E) {
;     ...
;         for (int t = 0; t < nt; t += 2) {
;             const bool last = (t == nt - 2);
;             const char* a1 = cA + (size_t)(t + 1) * kstep;
;             const char* a2 = last ? nA : cA + (size_t)(t + 2) * kstep; const char* b2 = last ? nB : cB + (size_t)(t + 2) * kstep;
;             const char* a3 = a2 + kstep; const char* b3 = b2 + kstep;
;             if (last && has_next) S.a_ready(nxt);
;             if constexpr (SP2) {
;             PG8_LDB(B0, 0, 0); PG8_LDB(B1, 0, 1); PG8_SCHED; PG8_LDA(At, 0, 0); PG8_STAGE(PG8_SA(1, 1), a1 + hstepA, voffA);
;             PG8_WAIT_V(8); PG8_WAIT_L(0); PG8_BAR; PG8_MMA(0, 0, At, B0); PG8_MMA(0, 1, At, B1); PG8_BAR; PG8_SCHED;
;             PG8_LDA(At, 0, 1); PG8_STAGE(PG8_SB(0, 0), b2, voffB); PG8_STAGE(PG8_SB(0, 1), b2 + hstepB, voffB); PG8_STAGE(PG8_SA(0, 0), a2, voffA);
;             PG8_WAIT_V(8); PG8_WAIT_L(0); PG8_BAR; PG8_MMA(1, 0, At, B0); PG8_MMA(1, 1, At, B1); PG8_BAR; PG8_SCHED;
.LBB0_380:
	s_add_i32 s84, s40, 2
	s_add_u32 s81, s78, 0x80
	s_addc_u32 s41, s79, 0
	s_add_i32 s85, 0, 0x10000
	s_cmp_eq_u32 s34, s40
	s_cselect_b32 s41, s45, s41
	s_cselect_b32 s40, s44, s81
	s_cselect_b32 s89, s75, s83
	s_cselect_b32 s88, s74, s77
	s_add_i32 s81, 0, 0x14000
	v_add_u32_e32 v140, s85, v249
	v_add_u32_e32 v156, s81, v249
	ds_read_b128 v[124:127], v140
	ds_read_b128 v[128:131], v140 offset:1024
	ds_read_b128 v[132:135], v140 offset:2048
	ds_read_b128 v[140:143], v140 offset:3072
	ds_read_b128 v[144:147], v156
	ds_read_b128 v[148:151], v156 offset:1024
	ds_read_b128 v[152:155], v156 offset:2048
	ds_read_b128 v[156:159], v156 offset:3072
	v_lshl_add_u64 v[208:209], s[78:79], 0, v[206:207]
	s_add_i32 m0, s12, 0xc000
	ds_read_b128 v[160:163], v251
	ds_read_b128 v[164:167], v251 offset:1024
	ds_read_b128 v[168:171], v251 offset:2048
	ds_read_b128 v[172:175], v251 offset:3072
	ds_read_b128 v[176:179], v251 offset:4096
	ds_read_b128 v[180:183], v251 offset:5120
	ds_read_b128 v[184:187], v251 offset:6144
	ds_read_b128 v[188:191], v251 offset:7168
	global_load_lds_dwordx4 v[208:209], off
	v_lshl_add_u64 v[208:209], s[78:79], 0, v[204:205]
	s_add_i32 m0, s12, 0xe000
	s_nop 0
	global_load_lds_dwordx4 v[208:209], off
	s_waitcnt vmcnt(8)
	s_waitcnt lgkmcnt(0)
	s_barrier
	s_setprio 1
	s_waitcnt lgkmcnt(0)
	v_mfma_f32_16x16x32_bf16 v[136:139], v[124:127], v[160:163], v[136:139]
	v_mfma_f32_16x16x32_bf16 v[120:123], v[132:135], v[160:163], v[120:123]
	v_mfma_f32_16x16x32_bf16 v[108:111], v[124:127], v[168:171], v[108:111]
	v_mfma_f32_16x16x32_bf16 v[104:107], v[132:135], v[168:171], v[104:107]
	v_mfma_f32_16x16x32_bf16 v[92:95], v[124:127], v[176:179], v[92:95]
	v_mfma_f32_16x16x32_bf16 v[88:91], v[132:135], v[176:179], v[88:91]
	v_mfma_f32_16x16x32_bf16 v[76:79], v[124:127], v[184:187], v[76:79]
	v_mfma_f32_16x16x32_bf16 v[72:75], v[132:135], v[184:187], v[72:75]
	v_mfma_f32_16x16x32_bf16 v[136:139], v[128:131], v[164:167], v[136:139]
	v_mfma_f32_16x16x32_bf16 v[120:123], v[140:143], v[164:167], v[120:123]
	v_mfma_f32_16x16x32_bf16 v[108:111], v[128:131], v[172:175], v[108:111]
	v_mfma_f32_16x16x32_bf16 v[104:107], v[140:143], v[172:175], v[104:107]
	v_mfma_f32_16x16x32_bf16 v[92:95], v[128:131], v[180:183], v[92:95]
	v_mfma_f32_16x16x32_bf16 v[88:91], v[140:143], v[180:183], v[88:91]
	v_mfma_f32_16x16x32_bf16 v[76:79], v[128:131], v[188:191], v[76:79]
	v_mfma_f32_16x16x32_bf16 v[72:75], v[140:143], v[188:191], v[72:75]
	v_mfma_f32_16x16x32_bf16 v[116:119], v[144:147], v[160:163], v[116:119]
	v_mfma_f32_16x16x32_bf16 v[112:115], v[152:155], v[160:163], v[112:115]
	v_mfma_f32_16x16x32_bf16 v[100:103], v[144:147], v[168:171], v[100:103]
	v_mfma_f32_16x16x32_bf16 v[96:99], v[152:155], v[168:171], v[96:99]
	v_mfma_f32_16x16x32_bf16 v[84:87], v[144:147], v[176:179], v[84:87]
	v_mfma_f32_16x16x32_bf16 v[80:83], v[152:155], v[176:179], v[80:83]
	v_mfma_f32_16x16x32_bf16 v[68:71], v[144:147], v[184:187], v[68:71]
	v_mfma_f32_16x16x32_bf16 v[64:67], v[152:155], v[184:187], v[64:67]
	v_mfma_f32_16x16x32_bf16 v[116:119], v[148:151], v[164:167], v[116:119]
	v_mfma_f32_16x16x32_bf16 v[112:115], v[156:159], v[164:167], v[112:115]
	v_mfma_f32_16x16x32_bf16 v[100:103], v[148:151], v[172:175], v[100:103]
	v_mfma_f32_16x16x32_bf16 v[96:99], v[156:159], v[172:175], v[96:99]
	v_mfma_f32_16x16x32_bf16 v[84:87], v[148:151], v[180:183], v[84:87]
	v_mfma_f32_16x16x32_bf16 v[80:83], v[156:159], v[180:183], v[80:83]
	v_mfma_f32_16x16x32_bf16 v[68:71], v[148:151], v[188:191], v[68:71]
	v_mfma_f32_16x16x32_bf16 v[64:67], v[156:159], v[188:191], v[64:67]
	s_setprio 0
	s_barrier
	s_add_i32 s85, s85, s11
	v_lshl_add_u64 v[208:209], s[88:89], 0, v[194:195]
	s_mov_b32 m0, s85
	ds_read_b128 v[160:163], v251 offset:16384
	ds_read_b128 v[164:167], v251 offset:17408
	ds_read_b128 v[168:171], v251 offset:18432
	ds_read_b128 v[172:175], v251 offset:19456
	ds_read_b128 v[176:179], v251 offset:20480
	ds_read_b128 v[180:183], v251 offset:21504
	ds_read_b128 v[184:187], v251 offset:22528
	ds_read_b128 v[188:191], v251 offset:23552
	global_load_lds_dwordx4 v[208:209], off
	s_add_i32 m0, s85, 0x2000
	v_lshl_add_u64 v[210:211], s[88:89], 0, v[202:203]
	s_add_u32 s88, s88, s24
	s_addc_u32 s89, s89, 0
	s_add_i32 s81, s81, s11
	global_load_lds_dwordx4 v[210:211], off
	v_lshl_add_u64 v[212:213], s[88:89], 0, v[194:195]
	s_mov_b32 m0, s81
	v_lshl_add_u64 v[214:215], s[88:89], 0, v[202:203]
	global_load_lds_dwordx4 v[212:213], off
	s_add_i32 m0, s81, 0x2000
	v_lshl_add_u64 v[216:217], s[40:41], 0, v[198:199]
	global_load_lds_dwordx4 v[214:215], off
	s_mov_b32 m0, s12
	v_lshl_add_u64 v[218:219], s[40:41], 0, v[200:201]
	global_load_lds_dwordx4 v[216:217], off
	s_mov_b32 m0, s13
	s_nop 0
	global_load_lds_dwordx4 v[218:219], off
	s_waitcnt vmcnt(8)
	s_waitcnt lgkmcnt(0)
	s_barrier
; #define PG8_STAGE(bufoff, gbase, voff) do { _Pragma("unroll") for (int _i = 0; _i < 2; ++_i) \
;         __builtin_amdgcn_global_load_lds((const unsigned*)((const char*)(gbase) + (voff)[_i]), (PG8_LAS unsigned*)(lds + (bufoff) + ldsw + _i * 8192), 16, 0, 0); } while (0)
; #define PG8_LDA(dst, b, h) do { _Pragma("unroll") for (int m = 0; m < 4; ++m) _Pragma("unroll") for (int k = 0; k < 2; ++k) dst[m][k] = *(const PG8_LAS bf16x8*)(lds + PG8_SA(b, h) + aoff + m * 2048 + k * 1024); } while (0)
; #define PG8_LDB(dst, b, h) do { _Pragma("unroll") for (int n = 0; n < 2; ++n) _Pragma("unroll") for (int k = 0; k < 2; ++k) dst[n][k] = *(const PG8_LAS bf16x8*)(lds + PG8_SB(b, h) + boff + n * 2048 + k * 1024); } while (0)
; #define PG8_MMA(ai, bj, At, Bt) do { __builtin_amdgcn_s_setprio(1); _Pragma("unroll") for (int m = 0; m < 4; ++m) _Pragma("unroll") for (int n = 0; n < 2; ++n) _Pragma("unroll") for (int k = 0; k < 2; ++k) \
;         acc[ai][bj][m][n] = __builtin_amdgcn_mfma_f32_16x16x32_bf16(Bt[n][k], At[m][k], acc[ai][bj][m][n], 0, 0, 0); __builtin_amdgcn_s_setprio(0); } while (0)
; #define PG8_WAIT_V(n) asm volatile("s_waitcnt vmcnt(" #n ")" ::: "memory")
; #define PG8_WAIT_L(n) asm volatile("s_waitcnt lgkmcnt(" #n ")" ::: "memory")
; #define PG8_BAR __builtin_amdgcn_s_barrier()
; #define PG8_SCHED __builtin_amdgcn_sched_barrier(0)
; template <class Epi, class Sched, bool ALIGN_EPI = false, bool SP2 = false>
; __device__ __forceinline__ void gemm_phase(PG8_LAS unsigned char* lds, const Gemm g, const Sched& S, const Epi& E) {
;     ...
;             PG8_WAIT_V(8); PG8_WAIT_L(0); PG8_BAR; PG8_MMA(1, 0, At, B0); PG8_MMA(1, 1, At, B1); PG8_BAR; PG8_SCHED;
;             PG8_LDB(B0, 1, 0); PG8_LDB(B1, 1, 1); PG8_SCHED; PG8_LDA(At, 1, 0); PG8_STAGE(PG8_SA(0, 1), a2 + hstepA, voffA);
;             PG8_WAIT_V(8); PG8_WAIT_L(0); PG8_BAR; PG8_MMA(0, 0, At, B0); PG8_MMA(0, 1, At, B1); PG8_BAR; PG8_SCHED;
	s_setprio 1
	s_waitcnt lgkmcnt(0)
	v_mfma_f32_16x16x32_bf16 v[60:63], v[124:127], v[160:163], v[60:63]
	v_mfma_f32_16x16x32_bf16 v[56:59], v[132:135], v[160:163], v[56:59]
	v_mfma_f32_16x16x32_bf16 v[44:47], v[124:127], v[168:171], v[44:47]
	v_mfma_f32_16x16x32_bf16 v[40:43], v[132:135], v[168:171], v[40:43]
	v_mfma_f32_16x16x32_bf16 v[28:31], v[124:127], v[176:179], v[28:31]
	v_mfma_f32_16x16x32_bf16 v[24:27], v[132:135], v[176:179], v[24:27]
	v_mfma_f32_16x16x32_bf16 v[12:15], v[124:127], v[184:187], v[12:15]
	v_mfma_f32_16x16x32_bf16 v[8:11], v[132:135], v[184:187], v[8:11]
	v_mfma_f32_16x16x32_bf16 v[60:63], v[128:131], v[164:167], v[60:63]
	v_mfma_f32_16x16x32_bf16 v[56:59], v[140:143], v[164:167], v[56:59]
	v_mfma_f32_16x16x32_bf16 v[44:47], v[128:131], v[172:175], v[44:47]
	v_mfma_f32_16x16x32_bf16 v[40:43], v[140:143], v[172:175], v[40:43]
	v_mfma_f32_16x16x32_bf16 v[28:31], v[128:131], v[180:183], v[28:31]
	v_mfma_f32_16x16x32_bf16 v[24:27], v[140:143], v[180:183], v[24:27]
	v_mfma_f32_16x16x32_bf16 v[12:15], v[128:131], v[188:191], v[12:15]
	v_mfma_f32_16x16x32_bf16 v[8:11], v[140:143], v[188:191], v[8:11]
	v_mfma_f32_16x16x32_bf16 v[52:55], v[144:147], v[160:163], v[52:55]
	v_mfma_f32_16x16x32_bf16 v[48:51], v[152:155], v[160:163], v[48:51]
	v_mfma_f32_16x16x32_bf16 v[36:39], v[144:147], v[168:171], v[36:39]
	v_mfma_f32_16x16x32_bf16 v[32:35], v[152:155], v[168:171], v[32:35]
	v_mfma_f32_16x16x32_bf16 v[20:23], v[144:147], v[176:179], v[20:23]
	v_mfma_f32_16x16x32_bf16 v[16:19], v[152:155], v[176:179], v[16:19]
	v_mfma_f32_16x16x32_bf16 v[4:7], v[144:147], v[184:187], v[4:7]
	v_mfma_f32_16x16x32_bf16 v[0:3], v[152:155], v[184:187], v[0:3]
	v_mfma_f32_16x16x32_bf16 v[52:55], v[148:151], v[164:167], v[52:55]
	v_mfma_f32_16x16x32_bf16 v[48:51], v[156:159], v[164:167], v[48:51]
	v_mfma_f32_16x16x32_bf16 v[36:39], v[148:151], v[172:175], v[36:39]
	v_mfma_f32_16x16x32_bf16 v[32:35], v[156:159], v[172:175], v[32:35]
	v_mfma_f32_16x16x32_bf16 v[20:23], v[148:151], v[180:183], v[20:23]
	v_mfma_f32_16x16x32_bf16 v[16:19], v[156:159], v[180:183], v[16:19]
	v_mfma_f32_16x16x32_bf16 v[4:7], v[148:151], v[188:191], v[4:7]
	v_mfma_f32_16x16x32_bf16 v[0:3], v[156:159], v[188:191], v[0:3]
	s_setprio 0
	s_barrier
	s_add_i32 s81, 0, 0x18000
	s_add_i32 s85, 0, 0x1c000
	v_add_u32_e32 v140, s81, v249
	v_add_u32_e32 v156, s85, v249
	ds_read_b128 v[124:127], v140
	ds_read_b128 v[128:131], v140 offset:1024
	ds_read_b128 v[132:135], v140 offset:2048
	ds_read_b128 v[140:143], v140 offset:3072
	ds_read_b128 v[144:147], v156
	ds_read_b128 v[148:151], v156 offset:1024
	ds_read_b128 v[152:155], v156 offset:2048
	ds_read_b128 v[156:159], v156 offset:3072
	s_add_u32 s40, s40, s24
	s_addc_u32 s41, s41, 0
	s_mov_b32 m0, s16
	v_lshl_add_u64 v[220:221], s[40:41], 0, v[198:199]
	ds_read_b128 v[160:163], v251 offset:32768
	ds_read_b128 v[164:167], v251 offset:33792
	ds_read_b128 v[168:171], v251 offset:34816
	ds_read_b128 v[172:175], v251 offset:35840
	ds_read_b128 v[176:179], v251 offset:36864
	ds_read_b128 v[180:183], v251 offset:37888
	ds_read_b128 v[184:187], v251 offset:38912
	ds_read_b128 v[188:191], v251 offset:39936
	global_load_lds_dwordx4 v[220:221], off
	v_lshl_add_u64 v[220:221], s[40:41], 0, v[200:201]
	s_mov_b32 m0, s17
	s_nop 0
	global_load_lds_dwordx4 v[220:221], off
	s_waitcnt vmcnt(8)
	s_waitcnt lgkmcnt(0)
	s_barrier
	s_setprio 1
	s_waitcnt lgkmcnt(0)
	v_mfma_f32_16x16x32_bf16 v[136:139], v[124:127], v[160:163], v[136:139]
	v_mfma_f32_16x16x32_bf16 v[120:123], v[132:135], v[160:163], v[120:123]
	v_mfma_f32_16x16x32_bf16 v[108:111], v[124:127], v[168:171], v[108:111]
	v_mfma_f32_16x16x32_bf16 v[104:107], v[132:135], v[168:171], v[104:107]
	v_mfma_f32_16x16x32_bf16 v[92:95], v[124:127], v[176:179], v[92:95]
	v_mfma_f32_16x16x32_bf16 v[88:91], v[132:135], v[176:179], v[88:91]
	v_mfma_f32_16x16x32_bf16 v[76:79], v[124:127], v[184:187], v[76:79]
	v_mfma_f32_16x16x32_bf16 v[72:75], v[132:135], v[184:187], v[72:75]
	v_mfma_f32_16x16x32_bf16 v[136:139], v[128:131], v[164:167], v[136:139]
	v_mfma_f32_16x16x32_bf16 v[120:123], v[140:143], v[164:167], v[120:123]
	v_mfma_f32_16x16x32_bf16 v[108:111], v[128:131], v[172:175], v[108:111]
	v_mfma_f32_16x16x32_bf16 v[104:107], v[140:143], v[172:175], v[104:107]
	v_mfma_f32_16x16x32_bf16 v[92:95], v[128:131], v[180:183], v[92:95]
	v_mfma_f32_16x16x32_bf16 v[88:91], v[140:143], v[180:183], v[88:91]
	v_mfma_f32_16x16x32_bf16 v[76:79], v[128:131], v[188:191], v[76:79]
	v_mfma_f32_16x16x32_bf16 v[72:75], v[140:143], v[188:191], v[72:75]
	v_mfma_f32_16x16x32_bf16 v[116:119], v[144:147], v[160:163], v[116:119]
	v_mfma_f32_16x16x32_bf16 v[112:115], v[152:155], v[160:163], v[112:115]
	v_mfma_f32_16x16x32_bf16 v[100:103], v[144:147], v[168:171], v[100:103]
	v_mfma_f32_16x16x32_bf16 v[96:99], v[152:155], v[168:171], v[96:99]
	v_mfma_f32_16x16x32_bf16 v[84:87], v[144:147], v[176:179], v[84:87]
	v_mfma_f32_16x16x32_bf16 v[80:83], v[152:155], v[176:179], v[80:83]
	v_mfma_f32_16x16x32_bf16 v[68:71], v[144:147], v[184:187], v[68:71]
	v_mfma_f32_16x16x32_bf16 v[64:67], v[152:155], v[184:187], v[64:67]
	v_mfma_f32_16x16x32_bf16 v[116:119], v[148:151], v[164:167], v[116:119]
	v_mfma_f32_16x16x32_bf16 v[112:115], v[156:159], v[164:167], v[112:115]
	v_mfma_f32_16x16x32_bf16 v[100:103], v[148:151], v[172:175], v[100:103]
	v_mfma_f32_16x16x32_bf16 v[96:99], v[156:159], v[172:175], v[96:99]
	v_mfma_f32_16x16x32_bf16 v[84:87], v[148:151], v[180:183], v[84:87]
	v_mfma_f32_16x16x32_bf16 v[80:83], v[156:159], v[180:183], v[80:83]
	v_mfma_f32_16x16x32_bf16 v[68:71], v[148:151], v[188:191], v[68:71]
	v_mfma_f32_16x16x32_bf16 v[64:67], v[156:159], v[188:191], v[64:67]
	s_setprio 0
	s_barrier
; #define PG8_STAGE(bufoff, gbase, voff) do { _Pragma("unroll") for (int _i = 0; _i < 2; ++_i) \
;         __builtin_amdgcn_global_load_lds((const unsigned*)((const char*)(gbase) + (voff)[_i]), (PG8_LAS unsigned*)(lds + (bufoff) + ldsw + _i * 8192), 16, 0, 0); } while (0)
; #define PG8_WAIT_V(n) asm volatile("s_waitcnt vmcnt(" #n ")" ::: "memory")
; #define PG8_WAIT_L(n) asm volatile("s_waitcnt lgkmcnt(" #n ")" ::: "memory")
; template <class Epi, class Sched, bool ALIGN_EPI = false, bool SP2 = false>
; __device__ __forceinline__ void gemm_phase(PG8_LAS unsigned char* lds, const Gemm g, const Sched& S, const Epi& E) {
;     ...
;             PG8_LDA(At, 1, 1); PG8_STAGE(PG8_SB(1, 0), b3, voffB); PG8_STAGE(PG8_SB(1, 1), b3 + hstepB, voffB); PG8_STAGE(PG8_SA(1, 0), a3, voffA);
;             PG8_WAIT_V(8); PG8_WAIT_L(0); PG8_BAR; PG8_MMA(1, 0, At, B0); PG8_MMA(1, 1, At, B1); PG8_BAR; PG8_SCHED;
;             } else {
;             PG8_LDB(B0, 0, 0); PG8_SCHED; PG8_LDA(At, 0, 0); PG8_STAGE(PG8_SA(1, 1), a1 + hstepA, voffA);
;             PG8_WAIT_L(8); PG8_BAR; PG8_WAIT_L(0); PG8_MMA(0, 0, At, B0); PG8_BAR; PG8_SCHED;
;             PG8_LDB(B1, 0, 1); PG8_STAGE(PG8_SB(0, 0), b2, voffB);
;             PG8_BAR; PG8_WAIT_L(0); PG8_MMA(0, 1, At, B1); PG8_BAR;
;             PG8_LDA(At, 0, 1); PG8_STAGE(PG8_SA(0, 0), a2, voffA);
;             PG8_BAR; PG8_WAIT_L(0); PG8_MMA(1, 0, At, B0); PG8_BAR; PG8_SCHED;
;             PG8_STAGE(PG8_SB(0, 1), b2 + hstepB, voffB);
;             PG8_WAIT_V(6); PG8_BAR; PG8_MMA(1, 1, At, B1); PG8_BAR;
;             PG8_LDB(B0, 1, 0); PG8_SCHED; PG8_LDA(At, 1, 0); PG8_STAGE(PG8_SA(0, 1), a2 + hstepA, voffA);
;             PG8_WAIT_L(8); PG8_BAR; PG8_WAIT_L(0); PG8_MMA(0, 0, At, B0); PG8_BAR; PG8_SCHED;
;             PG8_LDB(B1, 1, 1); PG8_STAGE(PG8_SB(1, 0), b3, voffB);
;             PG8_BAR; PG8_WAIT_L(0); PG8_MMA(0, 1, At, B1); PG8_BAR;
;             PG8_LDA(At, 1, 1); PG8_STAGE(PG8_SA(1, 0), a3, voffA);
;             PG8_BAR; PG8_WAIT_L(0); PG8_MMA(1, 0, At, B0); PG8_BAR; PG8_SCHED;
;             PG8_STAGE(PG8_SB(1, 1), b3 + hstepB, voffB);
;             PG8_WAIT_V(6); PG8_BAR; PG8_MMA(1, 1, At, B1); PG8_BAR;
;             }
;         }
;         if constexpr (ALIGN_EPI) { if (wr == 0) PG8_BAR; }
;         if constexpr (!Epi::AFTER_DRAIN) { E(acc, cur, wr, wc, fr, fq); S.done(cur); }
;         if (!has_next) break;
	s_add_i32 s40, s81, s11
	v_lshl_add_u64 v[208:209], v[208:209], 0, s[28:29]
	s_mov_b32 m0, s40
	ds_read_b128 v[160:163], v251 offset:49152
	ds_read_b128 v[164:167], v251 offset:50176
	ds_read_b128 v[168:171], v251 offset:51200
	ds_read_b128 v[172:175], v251 offset:52224
	ds_read_b128 v[176:179], v251 offset:53248
	ds_read_b128 v[180:183], v251 offset:54272
	ds_read_b128 v[184:187], v251 offset:55296
	ds_read_b128 v[188:191], v251 offset:56320
	global_load_lds_dwordx4 v[208:209], off
	v_lshl_add_u64 v[208:209], v[210:211], 0, s[28:29]
	s_add_i32 m0, s40, 0x2000
	s_add_i32 s40, s85, s11
	global_load_lds_dwordx4 v[208:209], off
	v_lshl_add_u64 v[208:209], v[212:213], 0, s[28:29]
	s_mov_b32 m0, s40
	s_nop 0
	global_load_lds_dwordx4 v[208:209], off
	v_lshl_add_u64 v[208:209], v[214:215], 0, s[28:29]
	s_add_i32 m0, s40, 0x2000
	s_nop 0
	global_load_lds_dwordx4 v[208:209], off
	v_lshl_add_u64 v[208:209], v[216:217], 0, s[28:29]
	s_mov_b32 m0, s26
	s_nop 0
	global_load_lds_dwordx4 v[208:209], off
	v_lshl_add_u64 v[208:209], v[218:219], 0, s[28:29]
	s_mov_b32 m0, s27
	s_nop 0
	global_load_lds_dwordx4 v[208:209], off
	s_waitcnt vmcnt(8)
	s_waitcnt lgkmcnt(0)
	s_barrier
	s_setprio 1
	s_waitcnt lgkmcnt(0)
	v_mfma_f32_16x16x32_bf16 v[60:63], v[124:127], v[160:163], v[60:63]
	v_mfma_f32_16x16x32_bf16 v[56:59], v[132:135], v[160:163], v[56:59]
	v_mfma_f32_16x16x32_bf16 v[44:47], v[124:127], v[168:171], v[44:47]
	v_mfma_f32_16x16x32_bf16 v[40:43], v[132:135], v[168:171], v[40:43]
	v_mfma_f32_16x16x32_bf16 v[28:31], v[124:127], v[176:179], v[28:31]
	v_mfma_f32_16x16x32_bf16 v[24:27], v[132:135], v[176:179], v[24:27]
	v_mfma_f32_16x16x32_bf16 v[12:15], v[124:127], v[184:187], v[12:15]
	v_mfma_f32_16x16x32_bf16 v[8:11], v[132:135], v[184:187], v[8:11]
	v_mfma_f32_16x16x32_bf16 v[60:63], v[128:131], v[164:167], v[60:63]
	v_mfma_f32_16x16x32_bf16 v[56:59], v[140:143], v[164:167], v[56:59]
	v_mfma_f32_16x16x32_bf16 v[44:47], v[128:131], v[172:175], v[44:47]
	v_mfma_f32_16x16x32_bf16 v[40:43], v[140:143], v[172:175], v[40:43]
	v_mfma_f32_16x16x32_bf16 v[28:31], v[128:131], v[180:183], v[28:31]
	v_mfma_f32_16x16x32_bf16 v[24:27], v[140:143], v[180:183], v[24:27]
	v_mfma_f32_16x16x32_bf16 v[12:15], v[128:131], v[188:191], v[12:15]
	v_mfma_f32_16x16x32_bf16 v[8:11], v[140:143], v[188:191], v[8:11]
	v_mfma_f32_16x16x32_bf16 v[52:55], v[144:147], v[160:163], v[52:55]
	v_mfma_f32_16x16x32_bf16 v[48:51], v[152:155], v[160:163], v[48:51]
	v_mfma_f32_16x16x32_bf16 v[36:39], v[144:147], v[168:171], v[36:39]
	v_mfma_f32_16x16x32_bf16 v[32:35], v[152:155], v[168:171], v[32:35]
	v_mfma_f32_16x16x32_bf16 v[20:23], v[144:147], v[176:179], v[20:23]
	v_mfma_f32_16x16x32_bf16 v[16:19], v[152:155], v[176:179], v[16:19]
	v_mfma_f32_16x16x32_bf16 v[4:7], v[144:147], v[184:187], v[4:7]
	v_mfma_f32_16x16x32_bf16 v[0:3], v[152:155], v[184:187], v[0:3]
	v_mfma_f32_16x16x32_bf16 v[52:55], v[148:151], v[164:167], v[52:55]
	v_mfma_f32_16x16x32_bf16 v[48:51], v[156:159], v[164:167], v[48:51]
	v_mfma_f32_16x16x32_bf16 v[36:39], v[148:151], v[172:175], v[36:39]
	v_mfma_f32_16x16x32_bf16 v[32:35], v[156:159], v[172:175], v[32:35]
	v_mfma_f32_16x16x32_bf16 v[20:23], v[148:151], v[180:183], v[20:23]
	v_mfma_f32_16x16x32_bf16 v[16:19], v[156:159], v[180:183], v[16:19]
	v_mfma_f32_16x16x32_bf16 v[4:7], v[148:151], v[188:191], v[4:7]
	v_mfma_f32_16x16x32_bf16 v[0:3], v[156:159], v[188:191], v[0:3]
	s_setprio 0
	s_barrier
	s_add_u32 s77, s77, 0x100
	s_addc_u32 s83, s83, 0
	s_add_u32 s78, s78, 0x100
	s_addc_u32 s79, s79, 0
	s_cmp_ge_u32 s84, s18
	s_mov_b32 s40, s84
	s_cbranch_scc0 .LBB0_380
	s_and_b64 vcc, exec, s[72:73]
	s_cbranch_vccz .LBB0_383
	s_barrier

; #define PG8_STAGE(bufoff, gbase, voff) do { _Pragma("unroll") for (int _i = 0; _i < 2; ++_i) \
;         __builtin_amdgcn_global_load_lds((const unsigned*)((const char*)(gbase) + (voff)[_i]), (PG8_LAS unsigned*)(lds + (bufoff) + ldsw + _i * 8192), 16, 0, 0); } while (0)
; #define PG8_LDA(dst, b, h) do { _Pragma("unroll") for (int m = 0; m < 4; ++m) _Pragma("unroll") for (int k = 0; k < 2; ++k) dst[m][k] = *(const PG8_LAS bf16x8*)(lds + PG8_SA(b, h) + aoff + m * 2048 + k * 1024); } while (0)
; #define PG8_LDB(dst, b, h) do { _Pragma("unroll") for (int n = 0; n < 2; ++n) _Pragma("unroll") for (int k = 0; k < 2; ++k) dst[n][k] = *(const PG8_LAS bf16x8*)(lds + PG8_SB(b, h) + boff + n * 2048 + k * 1024); } while (0)
; #define PG8_MMA(ai, bj, At, Bt) do { __builtin_amdgcn_s_setprio(1); _Pragma("unroll") for (int m = 0; m < 4; ++m) _Pragma("unroll") for (int n = 0; n < 2; ++n) _Pragma("unroll") for (int k = 0; k < 2; ++k) \
;         acc[ai][bj][m][n] = __builtin_amdgcn_mfma_f32_16x16x32_bf16(Bt[n][k], At[m][k], acc[ai][bj][m][n], 0, 0, 0); __builtin_amdgcn_s_setprio(0); } while (0)
; #define PG8_WAIT_V(n) asm volatile("s_waitcnt vmcnt(" #n ")" ::: "memory")
; #define PG8_BAR __builtin_amdgcn_s_barrier()
; template <class Epi, class Sched, bool ALIGN_EPI = false, bool SP2 = false>
; __device__ __forceinline__ void gemm_phase(PG8_LAS unsigned char* lds, const Gemm g, const Sched& S, const Epi& E) {
;     ...
;         for (int t = 0; t < nt; t += 2) {
;             const bool last = (t == nt - 2);
;             const char* a1 = cA + (size_t)(t + 1) * kstep;
;             const char* a2 = last ? nA : cA + (size_t)(t + 2) * kstep; const char* b2 = last ? nB : cB + (size_t)(t + 2) * kstep;
;             const char* a3 = a2 + kstep; const char* b3 = b2 + kstep;
;             if (last && has_next) S.a_ready(nxt);
;             if constexpr (SP2) {
;             PG8_LDB(B0, 0, 0); PG8_LDB(B1, 0, 1); PG8_SCHED; PG8_LDA(At, 0, 0); PG8_STAGE(PG8_SA(1, 1), a1 + hstepA, voffA);
;             PG8_WAIT_V(8); PG8_WAIT_L(0); PG8_BAR; PG8_MMA(0, 0, At, B0); PG8_MMA(0, 1, At, B1); PG8_BAR; PG8_SCHED;
;             PG8_LDA(At, 0, 1); PG8_STAGE(PG8_SB(0, 0), b2, voffB); PG8_STAGE(PG8_SB(0, 1), b2 + hstepB, voffB); PG8_STAGE(PG8_SA(0, 0), a2, voffA);
;             PG8_WAIT_V(8); PG8_WAIT_L(0); PG8_BAR; PG8_MMA(1, 0, At, B0); PG8_MMA(1, 1, At, B1); PG8_BAR; PG8_SCHED;
.LBB0_426:
	s_add_i32 s89, s40, 2
	s_add_u32 s81, s44, 0x80
	s_addc_u32 s41, s45, 0
	s_add_i32 s92, 0, 0x10000
	s_cmp_eq_u32 s50, s40
	s_cselect_b32 s41, s79, s41
	s_cselect_b32 s40, s78, s81
	v_add_u32_e32 v138, s92, v143
	s_cselect_b32 s91, s85, s88
	s_cselect_b32 s90, s84, s83
	s_add_i32 s81, 0, 0x14000
	ds_read_b128 v[144:147], v138
	ds_read_b128 v[148:151], v138 offset:1024
	ds_read_b128 v[152:155], v138 offset:2048
	ds_read_b128 v[160:163], v138 offset:3072
	v_add_u32_e32 v138, s81, v143
	ds_read_b128 v[164:167], v138
	ds_read_b128 v[168:171], v138 offset:1024
	ds_read_b128 v[172:175], v138 offset:2048
	ds_read_b128 v[176:179], v138 offset:3072
	v_lshl_add_u64 v[138:139], s[44:45], 0, v[136:137]
	s_add_i32 m0, s35, 0xc000
	ds_read_b128 v[180:183], v159
	ds_read_b128 v[184:187], v159 offset:1024
	ds_read_b128 v[188:191], v159 offset:2048
	ds_read_b128 v[198:201], v159 offset:3072
	ds_read_b128 v[202:205], v159 offset:4096
	ds_read_b128 v[206:209], v159 offset:5120
	ds_read_b128 v[210:213], v159 offset:6144
	ds_read_b128 v[214:217], v159 offset:7168
	global_load_lds_dwordx4 v[138:139], off
	v_lshl_add_u64 v[138:139], s[44:45], 0, v[134:135]
	s_add_i32 m0, s35, 0xe000
	s_nop 0
	global_load_lds_dwordx4 v[138:139], off
	s_waitcnt vmcnt(8)
	s_waitcnt lgkmcnt(0)
	s_barrier
	s_setprio 1
	s_waitcnt lgkmcnt(0)
	v_mfma_f32_16x16x32_bf16 v[124:127], v[144:147], v[180:183], v[124:127]
	v_mfma_f32_16x16x32_bf16 v[120:123], v[152:155], v[180:183], v[120:123]
	v_mfma_f32_16x16x32_bf16 v[108:111], v[144:147], v[188:191], v[108:111]
	v_mfma_f32_16x16x32_bf16 v[104:107], v[152:155], v[188:191], v[104:107]
	v_mfma_f32_16x16x32_bf16 v[92:95], v[144:147], v[202:205], v[92:95]
	v_mfma_f32_16x16x32_bf16 v[88:91], v[152:155], v[202:205], v[88:91]
	v_mfma_f32_16x16x32_bf16 v[76:79], v[144:147], v[210:213], v[76:79]
	v_mfma_f32_16x16x32_bf16 v[72:75], v[152:155], v[210:213], v[72:75]
	v_mfma_f32_16x16x32_bf16 v[124:127], v[148:151], v[184:187], v[124:127]
	v_mfma_f32_16x16x32_bf16 v[120:123], v[160:163], v[184:187], v[120:123]
	v_mfma_f32_16x16x32_bf16 v[108:111], v[148:151], v[198:201], v[108:111]
	v_mfma_f32_16x16x32_bf16 v[104:107], v[160:163], v[198:201], v[104:107]
	v_mfma_f32_16x16x32_bf16 v[92:95], v[148:151], v[206:209], v[92:95]
	v_mfma_f32_16x16x32_bf16 v[88:91], v[160:163], v[206:209], v[88:91]
	v_mfma_f32_16x16x32_bf16 v[76:79], v[148:151], v[214:217], v[76:79]
	v_mfma_f32_16x16x32_bf16 v[72:75], v[160:163], v[214:217], v[72:75]
	v_mfma_f32_16x16x32_bf16 v[116:119], v[164:167], v[180:183], v[116:119]
	v_mfma_f32_16x16x32_bf16 v[112:115], v[172:175], v[180:183], v[112:115]
	v_mfma_f32_16x16x32_bf16 v[100:103], v[164:167], v[188:191], v[100:103]
	v_mfma_f32_16x16x32_bf16 v[96:99], v[172:175], v[188:191], v[96:99]
	v_mfma_f32_16x16x32_bf16 v[84:87], v[164:167], v[202:205], v[84:87]
	v_mfma_f32_16x16x32_bf16 v[80:83], v[172:175], v[202:205], v[80:83]
	v_mfma_f32_16x16x32_bf16 v[68:71], v[164:167], v[210:213], v[68:71]
	v_mfma_f32_16x16x32_bf16 v[64:67], v[172:175], v[210:213], v[64:67]
	v_mfma_f32_16x16x32_bf16 v[116:119], v[168:171], v[184:187], v[116:119]
	v_mfma_f32_16x16x32_bf16 v[112:115], v[176:179], v[184:187], v[112:115]
	v_mfma_f32_16x16x32_bf16 v[100:103], v[168:171], v[198:201], v[100:103]
	v_mfma_f32_16x16x32_bf16 v[96:99], v[176:179], v[198:201], v[96:99]
	v_mfma_f32_16x16x32_bf16 v[84:87], v[168:171], v[206:209], v[84:87]
	v_mfma_f32_16x16x32_bf16 v[80:83], v[176:179], v[206:209], v[80:83]
	v_mfma_f32_16x16x32_bf16 v[68:71], v[168:171], v[214:217], v[68:71]
	v_mfma_f32_16x16x32_bf16 v[64:67], v[176:179], v[214:217], v[64:67]
	s_setprio 0
	s_barrier
	s_add_i32 s92, s92, s17
	v_lshl_add_u64 v[138:139], s[90:91], 0, v[194:195]
	s_mov_b32 m0, s92
	ds_read_b128 v[180:183], v159 offset:16384
	ds_read_b128 v[184:187], v159 offset:17408
	ds_read_b128 v[188:191], v159 offset:18432
	ds_read_b128 v[198:201], v159 offset:19456
	ds_read_b128 v[202:205], v159 offset:20480
	ds_read_b128 v[206:209], v159 offset:21504
	ds_read_b128 v[210:213], v159 offset:22528
	ds_read_b128 v[214:217], v159 offset:23552
	global_load_lds_dwordx4 v[138:139], off
	s_add_i32 m0, s92, 0x2000
	v_lshl_add_u64 v[156:157], s[90:91], 0, v[132:133]
	s_add_u32 s90, s90, s24
	s_addc_u32 s91, s91, 0
	s_add_i32 s81, s81, s17
	global_load_lds_dwordx4 v[156:157], off
	v_lshl_add_u64 v[218:219], s[90:91], 0, v[194:195]
	s_mov_b32 m0, s81
	v_lshl_add_u64 v[220:221], s[90:91], 0, v[132:133]
	global_load_lds_dwordx4 v[218:219], off
	s_add_i32 m0, s81, 0x2000
	v_lshl_add_u64 v[222:223], s[40:41], 0, v[128:129]
	global_load_lds_dwordx4 v[220:221], off
	s_mov_b32 m0, s35
	v_lshl_add_u64 v[224:225], s[40:41], 0, v[130:131]
	global_load_lds_dwordx4 v[222:223], off
	s_mov_b32 m0, s36
	s_nop 0
	global_load_lds_dwordx4 v[224:225], off
	s_waitcnt vmcnt(8)
	s_waitcnt lgkmcnt(0)
	s_barrier
; #define PG8_STAGE(bufoff, gbase, voff) do { _Pragma("unroll") for (int _i = 0; _i < 2; ++_i) \
;         __builtin_amdgcn_global_load_lds((const unsigned*)((const char*)(gbase) + (voff)[_i]), (PG8_LAS unsigned*)(lds + (bufoff) + ldsw + _i * 8192), 16, 0, 0); } while (0)
; #define PG8_LDA(dst, b, h) do { _Pragma("unroll") for (int m = 0; m < 4; ++m) _Pragma("unroll") for (int k = 0; k < 2; ++k) dst[m][k] = *(const PG8_LAS bf16x8*)(lds + PG8_SA(b, h) + aoff + m * 2048 + k * 1024); } while (0)
; #define PG8_LDB(dst, b, h) do { _Pragma("unroll") for (int n = 0; n < 2; ++n) _Pragma("unroll") for (int k = 0; k < 2; ++k) dst[n][k] = *(const PG8_LAS bf16x8*)(lds + PG8_SB(b, h) + boff + n * 2048 + k * 1024); } while (0)
; #define PG8_MMA(ai, bj, At, Bt) do { __builtin_amdgcn_s_setprio(1); _Pragma("unroll") for (int m = 0; m < 4; ++m) _Pragma("unroll") for (int n = 0; n < 2; ++n) _Pragma("unroll") for (int k = 0; k < 2; ++k) \
;         acc[ai][bj][m][n] = __builtin_amdgcn_mfma_f32_16x16x32_bf16(Bt[n][k], At[m][k], acc[ai][bj][m][n], 0, 0, 0); __builtin_amdgcn_s_setprio(0); } while (0)
; #define PG8_WAIT_V(n) asm volatile("s_waitcnt vmcnt(" #n ")" ::: "memory")
; #define PG8_WAIT_L(n) asm volatile("s_waitcnt lgkmcnt(" #n ")" ::: "memory")
; #define PG8_BAR __builtin_amdgcn_s_barrier()
; #define PG8_SCHED __builtin_amdgcn_sched_barrier(0)
; template <class Epi, class Sched, bool ALIGN_EPI = false, bool SP2 = false>
; __device__ __forceinline__ void gemm_phase(PG8_LAS unsigned char* lds, const Gemm g, const Sched& S, const Epi& E) {
;     ...
;             PG8_WAIT_V(8); PG8_WAIT_L(0); PG8_BAR; PG8_MMA(1, 0, At, B0); PG8_MMA(1, 1, At, B1); PG8_BAR; PG8_SCHED;
;             PG8_LDB(B0, 1, 0); PG8_LDB(B1, 1, 1); PG8_SCHED; PG8_LDA(At, 1, 0); PG8_STAGE(PG8_SA(0, 1), a2 + hstepA, voffA);
;             PG8_WAIT_V(8); PG8_WAIT_L(0); PG8_BAR; PG8_MMA(0, 0, At, B0); PG8_MMA(0, 1, At, B1); PG8_BAR; PG8_SCHED;
	s_setprio 1
	s_waitcnt lgkmcnt(0)
	v_mfma_f32_16x16x32_bf16 v[60:63], v[144:147], v[180:183], v[60:63]
	v_mfma_f32_16x16x32_bf16 v[56:59], v[152:155], v[180:183], v[56:59]
	v_mfma_f32_16x16x32_bf16 v[44:47], v[144:147], v[188:191], v[44:47]
	v_mfma_f32_16x16x32_bf16 v[40:43], v[152:155], v[188:191], v[40:43]
	v_mfma_f32_16x16x32_bf16 v[28:31], v[144:147], v[202:205], v[28:31]
	v_mfma_f32_16x16x32_bf16 v[24:27], v[152:155], v[202:205], v[24:27]
	v_mfma_f32_16x16x32_bf16 v[12:15], v[144:147], v[210:213], v[12:15]
	v_mfma_f32_16x16x32_bf16 v[8:11], v[152:155], v[210:213], v[8:11]
	v_mfma_f32_16x16x32_bf16 v[60:63], v[148:151], v[184:187], v[60:63]
	v_mfma_f32_16x16x32_bf16 v[56:59], v[160:163], v[184:187], v[56:59]
	v_mfma_f32_16x16x32_bf16 v[44:47], v[148:151], v[198:201], v[44:47]
	v_mfma_f32_16x16x32_bf16 v[40:43], v[160:163], v[198:201], v[40:43]
	v_mfma_f32_16x16x32_bf16 v[28:31], v[148:151], v[206:209], v[28:31]
	v_mfma_f32_16x16x32_bf16 v[24:27], v[160:163], v[206:209], v[24:27]
	v_mfma_f32_16x16x32_bf16 v[12:15], v[148:151], v[214:217], v[12:15]
	v_mfma_f32_16x16x32_bf16 v[8:11], v[160:163], v[214:217], v[8:11]
	v_mfma_f32_16x16x32_bf16 v[52:55], v[164:167], v[180:183], v[52:55]
	v_mfma_f32_16x16x32_bf16 v[48:51], v[172:175], v[180:183], v[48:51]
	v_mfma_f32_16x16x32_bf16 v[36:39], v[164:167], v[188:191], v[36:39]
	v_mfma_f32_16x16x32_bf16 v[32:35], v[172:175], v[188:191], v[32:35]
	v_mfma_f32_16x16x32_bf16 v[20:23], v[164:167], v[202:205], v[20:23]
	v_mfma_f32_16x16x32_bf16 v[16:19], v[172:175], v[202:205], v[16:19]
	v_mfma_f32_16x16x32_bf16 v[4:7], v[164:167], v[210:213], v[4:7]
	v_mfma_f32_16x16x32_bf16 v[0:3], v[172:175], v[210:213], v[0:3]
	v_mfma_f32_16x16x32_bf16 v[52:55], v[168:171], v[184:187], v[52:55]
	v_mfma_f32_16x16x32_bf16 v[48:51], v[176:179], v[184:187], v[48:51]
	v_mfma_f32_16x16x32_bf16 v[36:39], v[168:171], v[198:201], v[36:39]
	v_mfma_f32_16x16x32_bf16 v[32:35], v[176:179], v[198:201], v[32:35]
	v_mfma_f32_16x16x32_bf16 v[20:23], v[168:171], v[206:209], v[20:23]
	v_mfma_f32_16x16x32_bf16 v[16:19], v[176:179], v[206:209], v[16:19]
	v_mfma_f32_16x16x32_bf16 v[4:7], v[168:171], v[214:217], v[4:7]
	v_mfma_f32_16x16x32_bf16 v[0:3], v[176:179], v[214:217], v[0:3]
	s_setprio 0
	s_barrier
	s_add_i32 s81, 0, 0x18000
	v_add_u32_e32 v140, s81, v143
	s_add_i32 s90, 0, 0x1c000
	ds_read_b128 v[144:147], v140
	ds_read_b128 v[148:151], v140 offset:1024
	ds_read_b128 v[152:155], v140 offset:2048
	ds_read_b128 v[160:163], v140 offset:3072
	v_add_u32_e32 v140, s90, v143
	ds_read_b128 v[164:167], v140
	ds_read_b128 v[168:171], v140 offset:1024
	ds_read_b128 v[172:175], v140 offset:2048
	ds_read_b128 v[176:179], v140 offset:3072
	s_add_u32 s40, s40, s24
	s_addc_u32 s41, s41, 0
	s_mov_b32 m0, s37
	v_lshl_add_u64 v[242:243], s[40:41], 0, v[128:129]
	ds_read_b128 v[180:183], v159 offset:32768
	ds_read_b128 v[184:187], v159 offset:33792
	ds_read_b128 v[188:191], v159 offset:34816
	ds_read_b128 v[198:201], v159 offset:35840
	ds_read_b128 v[202:205], v159 offset:36864
	ds_read_b128 v[206:209], v159 offset:37888
	ds_read_b128 v[210:213], v159 offset:38912
	ds_read_b128 v[214:217], v159 offset:39936
	global_load_lds_dwordx4 v[242:243], off
	v_lshl_add_u64 v[242:243], s[40:41], 0, v[130:131]
	s_mov_b32 m0, s46
	s_nop 0
	global_load_lds_dwordx4 v[242:243], off
	s_waitcnt vmcnt(8)
	s_waitcnt lgkmcnt(0)
	s_barrier
	s_setprio 1
	s_waitcnt lgkmcnt(0)
	v_mfma_f32_16x16x32_bf16 v[124:127], v[144:147], v[180:183], v[124:127]
	v_mfma_f32_16x16x32_bf16 v[120:123], v[152:155], v[180:183], v[120:123]
	v_mfma_f32_16x16x32_bf16 v[108:111], v[144:147], v[188:191], v[108:111]
	v_mfma_f32_16x16x32_bf16 v[104:107], v[152:155], v[188:191], v[104:107]
	v_mfma_f32_16x16x32_bf16 v[92:95], v[144:147], v[202:205], v[92:95]
	v_mfma_f32_16x16x32_bf16 v[88:91], v[152:155], v[202:205], v[88:91]
	v_mfma_f32_16x16x32_bf16 v[76:79], v[144:147], v[210:213], v[76:79]
	v_mfma_f32_16x16x32_bf16 v[72:75], v[152:155], v[210:213], v[72:75]
	v_mfma_f32_16x16x32_bf16 v[124:127], v[148:151], v[184:187], v[124:127]
	v_mfma_f32_16x16x32_bf16 v[120:123], v[160:163], v[184:187], v[120:123]
	v_mfma_f32_16x16x32_bf16 v[108:111], v[148:151], v[198:201], v[108:111]
	v_mfma_f32_16x16x32_bf16 v[104:107], v[160:163], v[198:201], v[104:107]
	v_mfma_f32_16x16x32_bf16 v[92:95], v[148:151], v[206:209], v[92:95]
	v_mfma_f32_16x16x32_bf16 v[88:91], v[160:163], v[206:209], v[88:91]
	v_mfma_f32_16x16x32_bf16 v[76:79], v[148:151], v[214:217], v[76:79]
	v_mfma_f32_16x16x32_bf16 v[72:75], v[160:163], v[214:217], v[72:75]
	v_mfma_f32_16x16x32_bf16 v[116:119], v[164:167], v[180:183], v[116:119]
	v_mfma_f32_16x16x32_bf16 v[112:115], v[172:175], v[180:183], v[112:115]
	v_mfma_f32_16x16x32_bf16 v[100:103], v[164:167], v[188:191], v[100:103]
	v_mfma_f32_16x16x32_bf16 v[96:99], v[172:175], v[188:191], v[96:99]
	v_mfma_f32_16x16x32_bf16 v[84:87], v[164:167], v[202:205], v[84:87]
	v_mfma_f32_16x16x32_bf16 v[80:83], v[172:175], v[202:205], v[80:83]
	v_mfma_f32_16x16x32_bf16 v[68:71], v[164:167], v[210:213], v[68:71]
	v_mfma_f32_16x16x32_bf16 v[64:67], v[172:175], v[210:213], v[64:67]
	v_mfma_f32_16x16x32_bf16 v[116:119], v[168:171], v[184:187], v[116:119]
	v_mfma_f32_16x16x32_bf16 v[112:115], v[176:179], v[184:187], v[112:115]
	v_mfma_f32_16x16x32_bf16 v[100:103], v[168:171], v[198:201], v[100:103]
	v_mfma_f32_16x16x32_bf16 v[96:99], v[176:179], v[198:201], v[96:99]
	v_mfma_f32_16x16x32_bf16 v[84:87], v[168:171], v[206:209], v[84:87]
	v_mfma_f32_16x16x32_bf16 v[80:83], v[176:179], v[206:209], v[80:83]
	v_mfma_f32_16x16x32_bf16 v[68:71], v[168:171], v[214:217], v[68:71]
	v_mfma_f32_16x16x32_bf16 v[64:67], v[176:179], v[214:217], v[64:67]
	s_setprio 0
	s_barrier
; #define PG8_STAGE(bufoff, gbase, voff) do { _Pragma("unroll") for (int _i = 0; _i < 2; ++_i) \
;         __builtin_amdgcn_global_load_lds((const unsigned*)((const char*)(gbase) + (voff)[_i]), (PG8_LAS unsigned*)(lds + (bufoff) + ldsw + _i * 8192), 16, 0, 0); } while (0)
; #define PG8_WAIT_V(n) asm volatile("s_waitcnt vmcnt(" #n ")" ::: "memory")
; #define PG8_WAIT_L(n) asm volatile("s_waitcnt lgkmcnt(" #n ")" ::: "memory")
; template <class Epi, class Sched, bool ALIGN_EPI = false, bool SP2 = false>
; __device__ __forceinline__ void gemm_phase(PG8_LAS unsigned char* lds, const Gemm g, const Sched& S, const Epi& E) {
;     ...
;             PG8_LDA(At, 1, 1); PG8_STAGE(PG8_SB(1, 0), b3, voffB); PG8_STAGE(PG8_SB(1, 1), b3 + hstepB, voffB); PG8_STAGE(PG8_SA(1, 0), a3, voffA);
;             PG8_WAIT_V(8); PG8_WAIT_L(0); PG8_BAR; PG8_MMA(1, 0, At, B0); PG8_MMA(1, 1, At, B1); PG8_BAR; PG8_SCHED;
;             } else {
;             PG8_LDB(B0, 0, 0); PG8_SCHED; PG8_LDA(At, 0, 0); PG8_STAGE(PG8_SA(1, 1), a1 + hstepA, voffA);
;             PG8_WAIT_L(8); PG8_BAR; PG8_WAIT_L(0); PG8_MMA(0, 0, At, B0); PG8_BAR; PG8_SCHED;
;             PG8_LDB(B1, 0, 1); PG8_STAGE(PG8_SB(0, 0), b2, voffB);
;             PG8_BAR; PG8_WAIT_L(0); PG8_MMA(0, 1, At, B1); PG8_BAR;
;             PG8_LDA(At, 0, 1); PG8_STAGE(PG8_SA(0, 0), a2, voffA);
;             PG8_BAR; PG8_WAIT_L(0); PG8_MMA(1, 0, At, B0); PG8_BAR; PG8_SCHED;
;             PG8_STAGE(PG8_SB(0, 1), b2 + hstepB, voffB);
;             PG8_WAIT_V(6); PG8_BAR; PG8_MMA(1, 1, At, B1); PG8_BAR;
;             PG8_LDB(B0, 1, 0); PG8_SCHED; PG8_LDA(At, 1, 0); PG8_STAGE(PG8_SA(0, 1), a2 + hstepA, voffA);
;             PG8_WAIT_L(8); PG8_BAR; PG8_WAIT_L(0); PG8_MMA(0, 0, At, B0); PG8_BAR; PG8_SCHED;
;             PG8_LDB(B1, 1, 1); PG8_STAGE(PG8_SB(1, 0), b3, voffB);
;             PG8_BAR; PG8_WAIT_L(0); PG8_MMA(0, 1, At, B1); PG8_BAR;
;             PG8_LDA(At, 1, 1); PG8_STAGE(PG8_SA(1, 0), a3, voffA);
;             PG8_BAR; PG8_WAIT_L(0); PG8_MMA(1, 0, At, B0); PG8_BAR; PG8_SCHED;
;             PG8_STAGE(PG8_SB(1, 1), b3 + hstepB, voffB);
;             PG8_WAIT_V(6); PG8_BAR; PG8_MMA(1, 1, At, B1); PG8_BAR;
;             }
;         }
;         if constexpr (ALIGN_EPI) { if (wr == 0) PG8_BAR; }
;         if constexpr (!Epi::AFTER_DRAIN) { E(acc, cur, wr, wc, fr, fq); S.done(cur); }
;         if (!has_next) break;
	s_add_i32 s40, s81, s17
	v_lshl_add_u64 v[138:139], v[138:139], 0, s[28:29]
	s_mov_b32 m0, s40
	ds_read_b128 v[180:183], v159 offset:49152
	ds_read_b128 v[184:187], v159 offset:50176
	ds_read_b128 v[188:191], v159 offset:51200
	ds_read_b128 v[198:201], v159 offset:52224
	ds_read_b128 v[202:205], v159 offset:53248
	ds_read_b128 v[206:209], v159 offset:54272
	ds_read_b128 v[210:213], v159 offset:55296
	ds_read_b128 v[214:217], v159 offset:56320
	global_load_lds_dwordx4 v[138:139], off
	v_lshl_add_u64 v[138:139], v[156:157], 0, s[28:29]
	s_add_i32 m0, s40, 0x2000
	s_add_i32 s40, s90, s17
	global_load_lds_dwordx4 v[138:139], off
	v_lshl_add_u64 v[138:139], v[218:219], 0, s[28:29]
	s_mov_b32 m0, s40
	s_nop 0
	global_load_lds_dwordx4 v[138:139], off
	v_lshl_add_u64 v[138:139], v[220:221], 0, s[28:29]
	s_add_i32 m0, s40, 0x2000
	s_nop 0
	global_load_lds_dwordx4 v[138:139], off
	v_lshl_add_u64 v[138:139], v[222:223], 0, s[28:29]
	s_mov_b32 m0, s48
	s_nop 0
	global_load_lds_dwordx4 v[138:139], off
	v_lshl_add_u64 v[138:139], v[224:225], 0, s[28:29]
	s_mov_b32 m0, s49
	s_nop 0
	global_load_lds_dwordx4 v[138:139], off
	s_waitcnt vmcnt(8)
	s_waitcnt lgkmcnt(0)
	s_barrier
	s_setprio 1
	s_waitcnt lgkmcnt(0)
	v_mfma_f32_16x16x32_bf16 v[60:63], v[144:147], v[180:183], v[60:63]
	v_mfma_f32_16x16x32_bf16 v[56:59], v[152:155], v[180:183], v[56:59]
	v_mfma_f32_16x16x32_bf16 v[44:47], v[144:147], v[188:191], v[44:47]
	v_mfma_f32_16x16x32_bf16 v[40:43], v[152:155], v[188:191], v[40:43]
	v_mfma_f32_16x16x32_bf16 v[28:31], v[144:147], v[202:205], v[28:31]
	v_mfma_f32_16x16x32_bf16 v[24:27], v[152:155], v[202:205], v[24:27]
	v_mfma_f32_16x16x32_bf16 v[12:15], v[144:147], v[210:213], v[12:15]
	v_mfma_f32_16x16x32_bf16 v[8:11], v[152:155], v[210:213], v[8:11]
	v_mfma_f32_16x16x32_bf16 v[60:63], v[148:151], v[184:187], v[60:63]
	v_mfma_f32_16x16x32_bf16 v[56:59], v[160:163], v[184:187], v[56:59]
	v_mfma_f32_16x16x32_bf16 v[44:47], v[148:151], v[198:201], v[44:47]
	v_mfma_f32_16x16x32_bf16 v[40:43], v[160:163], v[198:201], v[40:43]
	v_mfma_f32_16x16x32_bf16 v[28:31], v[148:151], v[206:209], v[28:31]
	v_mfma_f32_16x16x32_bf16 v[24:27], v[160:163], v[206:209], v[24:27]
	v_mfma_f32_16x16x32_bf16 v[12:15], v[148:151], v[214:217], v[12:15]
	v_mfma_f32_16x16x32_bf16 v[8:11], v[160:163], v[214:217], v[8:11]
	v_mfma_f32_16x16x32_bf16 v[52:55], v[164:167], v[180:183], v[52:55]
	v_mfma_f32_16x16x32_bf16 v[48:51], v[172:175], v[180:183], v[48:51]
	v_mfma_f32_16x16x32_bf16 v[36:39], v[164:167], v[188:191], v[36:39]
	v_mfma_f32_16x16x32_bf16 v[32:35], v[172:175], v[188:191], v[32:35]
	v_mfma_f32_16x16x32_bf16 v[20:23], v[164:167], v[202:205], v[20:23]
	v_mfma_f32_16x16x32_bf16 v[16:19], v[172:175], v[202:205], v[16:19]
	v_mfma_f32_16x16x32_bf16 v[4:7], v[164:167], v[210:213], v[4:7]
	v_mfma_f32_16x16x32_bf16 v[0:3], v[172:175], v[210:213], v[0:3]
	v_mfma_f32_16x16x32_bf16 v[52:55], v[168:171], v[184:187], v[52:55]
	v_mfma_f32_16x16x32_bf16 v[48:51], v[176:179], v[184:187], v[48:51]
	v_mfma_f32_16x16x32_bf16 v[36:39], v[168:171], v[198:201], v[36:39]
	v_mfma_f32_16x16x32_bf16 v[32:35], v[176:179], v[198:201], v[32:35]
	v_mfma_f32_16x16x32_bf16 v[20:23], v[168:171], v[206:209], v[20:23]
	v_mfma_f32_16x16x32_bf16 v[16:19], v[176:179], v[206:209], v[16:19]
	v_mfma_f32_16x16x32_bf16 v[4:7], v[168:171], v[214:217], v[4:7]
	v_mfma_f32_16x16x32_bf16 v[0:3], v[176:179], v[214:217], v[0:3]
	s_setprio 0
	s_barrier
	s_add_u32 s83, s83, 0x100
	s_addc_u32 s88, s88, 0
	s_add_u32 s44, s44, 0x100
	s_addc_u32 s45, s45, 0
	s_cmp_ge_u32 s89, s47
	s_mov_b32 s40, s89
	s_cbranch_scc0 .LBB0_426
	s_and_b64 vcc, exec, s[72:73]
	s_cbranch_vccz .LBB0_429
	s_barrier

; #define PG8_STAGE(bufoff, gbase, voff) do { _Pragma("unroll") for (int _i = 0; _i < 2; ++_i) \
;         __builtin_amdgcn_global_load_lds((const unsigned*)((const char*)(gbase) + (voff)[_i]), (PG8_LAS unsigned*)(lds + (bufoff) + ldsw + _i * 8192), 16, 0, 0); } while (0)
; #define PG8_LDA(dst, b, h) do { _Pragma("unroll") for (int m = 0; m < 4; ++m) _Pragma("unroll") for (int k = 0; k < 2; ++k) dst[m][k] = *(const PG8_LAS bf16x8*)(lds + PG8_SA(b, h) + aoff + m * 2048 + k * 1024); } while (0)
; #define PG8_LDB(dst, b, h) do { _Pragma("unroll") for (int n = 0; n < 2; ++n) _Pragma("unroll") for (int k = 0; k < 2; ++k) dst[n][k] = *(const PG8_LAS bf16x8*)(lds + PG8_SB(b, h) + boff + n * 2048 + k * 1024); } while (0)
; #define PG8_MMA(ai, bj, At, Bt) do { __builtin_amdgcn_s_setprio(1); _Pragma("unroll") for (int m = 0; m < 4; ++m) _Pragma("unroll") for (int n = 0; n < 2; ++n) _Pragma("unroll") for (int k = 0; k < 2; ++k) \
;         acc[ai][bj][m][n] = __builtin_amdgcn_mfma_f32_16x16x32_bf16(Bt[n][k], At[m][k], acc[ai][bj][m][n], 0, 0, 0); __builtin_amdgcn_s_setprio(0); } while (0)
; #define PG8_WAIT_V(n) asm volatile("s_waitcnt vmcnt(" #n ")" ::: "memory")
; #define PG8_BAR __builtin_amdgcn_s_barrier()
; template <class Epi, class Sched, bool ALIGN_EPI = false, bool SP2 = false>
; __device__ __forceinline__ void gemm_phase(PG8_LAS unsigned char* lds, const Gemm g, const Sched& S, const Epi& E) {
;     ...
;         for (int t = 0; t < nt; t += 2) {
;             const bool last = (t == nt - 2);
;             const char* a1 = cA + (size_t)(t + 1) * kstep;
;             const char* a2 = last ? nA : cA + (size_t)(t + 2) * kstep; const char* b2 = last ? nB : cB + (size_t)(t + 2) * kstep;
;             const char* a3 = a2 + kstep; const char* b3 = b2 + kstep;
;             if (last && has_next) S.a_ready(nxt);
;             if constexpr (SP2) {
;             PG8_LDB(B0, 0, 0); PG8_LDB(B1, 0, 1); PG8_SCHED; PG8_LDA(At, 0, 0); PG8_STAGE(PG8_SA(1, 1), a1 + hstepA, voffA);
;             PG8_WAIT_V(8); PG8_WAIT_L(0); PG8_BAR; PG8_MMA(0, 0, At, B0); PG8_MMA(0, 1, At, B1); PG8_BAR; PG8_SCHED;
;             PG8_LDA(At, 0, 1); PG8_STAGE(PG8_SB(0, 0), b2, voffB); PG8_STAGE(PG8_SB(0, 1), b2 + hstepB, voffB); PG8_STAGE(PG8_SA(0, 0), a2, voffA);
;             PG8_WAIT_V(8); PG8_WAIT_L(0); PG8_BAR; PG8_MMA(1, 0, At, B0); PG8_MMA(1, 1, At, B1); PG8_BAR; PG8_SCHED;
.LBB0_460:
	s_add_i32 s76, s40, 2
	s_add_u32 s77, s44, 0x80
	s_addc_u32 s41, s45, 0
	s_add_i32 s81, 0, 0x10000
	s_cmp_eq_u32 s13, s40
	s_cselect_b32 s41, s87, s41
	s_cselect_b32 s40, s86, s77
	s_cselect_b32 s91, s79, vcc_hi
	s_cselect_b32 s90, s78, vcc_lo
	s_add_i32 s77, 0, 0x14000
	v_add_u32_e32 v154, s81, v165
	v_add_u32_e32 v162, s77, v165
	ds_read_b128 v[142:145], v154
	ds_read_b128 v[146:149], v154 offset:1024
	ds_read_b128 v[150:153], v154 offset:2048
	ds_read_b128 v[154:157], v154 offset:3072
	ds_read_b128 v[158:161], v162
	ds_read_b128 v[168:171], v162 offset:1024
	ds_read_b128 v[172:175], v162 offset:2048
	ds_read_b128 v[176:179], v162 offset:3072
	v_lshl_add_u64 v[162:163], s[44:45], 0, v[140:141]
	s_add_i32 m0, s57, 0xc000
	ds_read_b128 v[180:183], v167
	ds_read_b128 v[184:187], v167 offset:1024
	ds_read_b128 v[188:191], v167 offset:2048
	ds_read_b128 v[198:201], v167 offset:3072
	ds_read_b128 v[202:205], v167 offset:4096
	ds_read_b128 v[206:209], v167 offset:5120
	ds_read_b128 v[210:213], v167 offset:6144
	ds_read_b128 v[214:217], v167 offset:7168
	global_load_lds_dwordx4 v[162:163], off
	v_lshl_add_u64 v[162:163], s[44:45], 0, v[138:139]
	s_add_i32 m0, s57, 0xe000
	s_nop 0
	global_load_lds_dwordx4 v[162:163], off
	s_waitcnt vmcnt(8)
	s_waitcnt lgkmcnt(0)
	s_barrier
	s_setprio 1
	s_waitcnt lgkmcnt(0)
	v_mfma_f32_16x16x32_bf16 v[124:127], v[142:145], v[180:183], v[124:127]
	v_mfma_f32_16x16x32_bf16 v[120:123], v[150:153], v[180:183], v[120:123]
	v_mfma_f32_16x16x32_bf16 v[108:111], v[142:145], v[188:191], v[108:111]
	v_mfma_f32_16x16x32_bf16 v[104:107], v[150:153], v[188:191], v[104:107]
	v_mfma_f32_16x16x32_bf16 v[92:95], v[142:145], v[202:205], v[92:95]
	v_mfma_f32_16x16x32_bf16 v[88:91], v[150:153], v[202:205], v[88:91]
	v_mfma_f32_16x16x32_bf16 v[76:79], v[142:145], v[210:213], v[76:79]
	v_mfma_f32_16x16x32_bf16 v[72:75], v[150:153], v[210:213], v[72:75]
	v_mfma_f32_16x16x32_bf16 v[124:127], v[146:149], v[184:187], v[124:127]
	v_mfma_f32_16x16x32_bf16 v[120:123], v[154:157], v[184:187], v[120:123]
	v_mfma_f32_16x16x32_bf16 v[108:111], v[146:149], v[198:201], v[108:111]
	v_mfma_f32_16x16x32_bf16 v[104:107], v[154:157], v[198:201], v[104:107]
	v_mfma_f32_16x16x32_bf16 v[92:95], v[146:149], v[206:209], v[92:95]
	v_mfma_f32_16x16x32_bf16 v[88:91], v[154:157], v[206:209], v[88:91]
	v_mfma_f32_16x16x32_bf16 v[76:79], v[146:149], v[214:217], v[76:79]
	v_mfma_f32_16x16x32_bf16 v[72:75], v[154:157], v[214:217], v[72:75]
	v_mfma_f32_16x16x32_bf16 v[116:119], v[158:161], v[180:183], v[116:119]
	v_mfma_f32_16x16x32_bf16 v[112:115], v[172:175], v[180:183], v[112:115]
	v_mfma_f32_16x16x32_bf16 v[100:103], v[158:161], v[188:191], v[100:103]
	v_mfma_f32_16x16x32_bf16 v[96:99], v[172:175], v[188:191], v[96:99]
	v_mfma_f32_16x16x32_bf16 v[84:87], v[158:161], v[202:205], v[84:87]
	v_mfma_f32_16x16x32_bf16 v[80:83], v[172:175], v[202:205], v[80:83]
	v_mfma_f32_16x16x32_bf16 v[68:71], v[158:161], v[210:213], v[68:71]
	v_mfma_f32_16x16x32_bf16 v[64:67], v[172:175], v[210:213], v[64:67]
	v_mfma_f32_16x16x32_bf16 v[116:119], v[168:171], v[184:187], v[116:119]
	v_mfma_f32_16x16x32_bf16 v[112:115], v[176:179], v[184:187], v[112:115]
	v_mfma_f32_16x16x32_bf16 v[100:103], v[168:171], v[198:201], v[100:103]
	v_mfma_f32_16x16x32_bf16 v[96:99], v[176:179], v[198:201], v[96:99]
	v_mfma_f32_16x16x32_bf16 v[84:87], v[168:171], v[206:209], v[84:87]
	v_mfma_f32_16x16x32_bf16 v[80:83], v[176:179], v[206:209], v[80:83]
	v_mfma_f32_16x16x32_bf16 v[68:71], v[168:171], v[214:217], v[68:71]
	v_mfma_f32_16x16x32_bf16 v[64:67], v[176:179], v[214:217], v[64:67]
	s_setprio 0
	s_barrier
	s_add_i32 s81, s81, s56
	v_lshl_add_u64 v[162:163], s[90:91], 0, v[130:131]
	s_mov_b32 m0, s81
	ds_read_b128 v[180:183], v167 offset:16384
	ds_read_b128 v[184:187], v167 offset:17408
	ds_read_b128 v[188:191], v167 offset:18432
	ds_read_b128 v[198:201], v167 offset:19456
	ds_read_b128 v[202:205], v167 offset:20480
	ds_read_b128 v[206:209], v167 offset:21504
	ds_read_b128 v[210:213], v167 offset:22528
	ds_read_b128 v[214:217], v167 offset:23552
	global_load_lds_dwordx4 v[162:163], off
	s_add_i32 m0, s81, 0x2000
	v_lshl_add_u64 v[218:219], s[90:91], 0, v[134:135]
	s_add_u32 s90, s90, s24
	s_addc_u32 s91, s91, 0
	s_add_i32 s77, s77, s56
	global_load_lds_dwordx4 v[218:219], off
	v_lshl_add_u64 v[220:221], s[90:91], 0, v[130:131]
	s_mov_b32 m0, s77
	v_lshl_add_u64 v[222:223], s[90:91], 0, v[134:135]
	global_load_lds_dwordx4 v[220:221], off
	s_add_i32 m0, s77, 0x2000
	v_lshl_add_u64 v[224:225], s[40:41], 0, v[128:129]
	global_load_lds_dwordx4 v[222:223], off
	s_mov_b32 m0, s57
	v_lshl_add_u64 v[250:251], s[40:41], 0, v[132:133]
	global_load_lds_dwordx4 v[224:225], off
	s_mov_b32 m0, s48
	s_nop 0
	global_load_lds_dwordx4 v[250:251], off
	s_waitcnt vmcnt(8)
	s_waitcnt lgkmcnt(0)
	s_barrier
; #define PG8_STAGE(bufoff, gbase, voff) do { _Pragma("unroll") for (int _i = 0; _i < 2; ++_i) \
;         __builtin_amdgcn_global_load_lds((const unsigned*)((const char*)(gbase) + (voff)[_i]), (PG8_LAS unsigned*)(lds + (bufoff) + ldsw + _i * 8192), 16, 0, 0); } while (0)
; #define PG8_LDA(dst, b, h) do { _Pragma("unroll") for (int m = 0; m < 4; ++m) _Pragma("unroll") for (int k = 0; k < 2; ++k) dst[m][k] = *(const PG8_LAS bf16x8*)(lds + PG8_SA(b, h) + aoff + m * 2048 + k * 1024); } while (0)
; #define PG8_LDB(dst, b, h) do { _Pragma("unroll") for (int n = 0; n < 2; ++n) _Pragma("unroll") for (int k = 0; k < 2; ++k) dst[n][k] = *(const PG8_LAS bf16x8*)(lds + PG8_SB(b, h) + boff + n * 2048 + k * 1024); } while (0)
; #define PG8_MMA(ai, bj, At, Bt) do { __builtin_amdgcn_s_setprio(1); _Pragma("unroll") for (int m = 0; m < 4; ++m) _Pragma("unroll") for (int n = 0; n < 2; ++n) _Pragma("unroll") for (int k = 0; k < 2; ++k) \
;         acc[ai][bj][m][n] = __builtin_amdgcn_mfma_f32_16x16x32_bf16(Bt[n][k], At[m][k], acc[ai][bj][m][n], 0, 0, 0); __builtin_amdgcn_s_setprio(0); } while (0)
; #define PG8_WAIT_V(n) asm volatile("s_waitcnt vmcnt(" #n ")" ::: "memory")
; #define PG8_WAIT_L(n) asm volatile("s_waitcnt lgkmcnt(" #n ")" ::: "memory")
; #define PG8_BAR __builtin_amdgcn_s_barrier()
; #define PG8_SCHED __builtin_amdgcn_sched_barrier(0)
; template <class Epi, class Sched, bool ALIGN_EPI = false, bool SP2 = false>
; __device__ __forceinline__ void gemm_phase(PG8_LAS unsigned char* lds, const Gemm g, const Sched& S, const Epi& E) {
;     ...
;             PG8_WAIT_V(8); PG8_WAIT_L(0); PG8_BAR; PG8_MMA(1, 0, At, B0); PG8_MMA(1, 1, At, B1); PG8_BAR; PG8_SCHED;
;             PG8_LDB(B0, 1, 0); PG8_LDB(B1, 1, 1); PG8_SCHED; PG8_LDA(At, 1, 0); PG8_STAGE(PG8_SA(0, 1), a2 + hstepA, voffA);
;             PG8_WAIT_V(8); PG8_WAIT_L(0); PG8_BAR; PG8_MMA(0, 0, At, B0); PG8_MMA(0, 1, At, B1); PG8_BAR; PG8_SCHED;
	s_setprio 1
	s_waitcnt lgkmcnt(0)
	v_mfma_f32_16x16x32_bf16 v[60:63], v[142:145], v[180:183], v[60:63]
	v_mfma_f32_16x16x32_bf16 v[56:59], v[150:153], v[180:183], v[56:59]
	v_mfma_f32_16x16x32_bf16 v[44:47], v[142:145], v[188:191], v[44:47]
	v_mfma_f32_16x16x32_bf16 v[40:43], v[150:153], v[188:191], v[40:43]
	v_mfma_f32_16x16x32_bf16 v[28:31], v[142:145], v[202:205], v[28:31]
	v_mfma_f32_16x16x32_bf16 v[24:27], v[150:153], v[202:205], v[24:27]
	v_mfma_f32_16x16x32_bf16 v[12:15], v[142:145], v[210:213], v[12:15]
	v_mfma_f32_16x16x32_bf16 v[8:11], v[150:153], v[210:213], v[8:11]
	v_mfma_f32_16x16x32_bf16 v[60:63], v[146:149], v[184:187], v[60:63]
	v_mfma_f32_16x16x32_bf16 v[56:59], v[154:157], v[184:187], v[56:59]
	v_mfma_f32_16x16x32_bf16 v[44:47], v[146:149], v[198:201], v[44:47]
	v_mfma_f32_16x16x32_bf16 v[40:43], v[154:157], v[198:201], v[40:43]
	v_mfma_f32_16x16x32_bf16 v[28:31], v[146:149], v[206:209], v[28:31]
	v_mfma_f32_16x16x32_bf16 v[24:27], v[154:157], v[206:209], v[24:27]
	v_mfma_f32_16x16x32_bf16 v[12:15], v[146:149], v[214:217], v[12:15]
	v_mfma_f32_16x16x32_bf16 v[8:11], v[154:157], v[214:217], v[8:11]
	v_mfma_f32_16x16x32_bf16 v[52:55], v[158:161], v[180:183], v[52:55]
	v_mfma_f32_16x16x32_bf16 v[48:51], v[172:175], v[180:183], v[48:51]
	v_mfma_f32_16x16x32_bf16 v[36:39], v[158:161], v[188:191], v[36:39]
	v_mfma_f32_16x16x32_bf16 v[32:35], v[172:175], v[188:191], v[32:35]
	v_mfma_f32_16x16x32_bf16 v[20:23], v[158:161], v[202:205], v[20:23]
	v_mfma_f32_16x16x32_bf16 v[16:19], v[172:175], v[202:205], v[16:19]
	v_mfma_f32_16x16x32_bf16 v[4:7], v[158:161], v[210:213], v[4:7]
	v_mfma_f32_16x16x32_bf16 v[0:3], v[172:175], v[210:213], v[0:3]
	v_mfma_f32_16x16x32_bf16 v[52:55], v[168:171], v[184:187], v[52:55]
	v_mfma_f32_16x16x32_bf16 v[48:51], v[176:179], v[184:187], v[48:51]
	v_mfma_f32_16x16x32_bf16 v[36:39], v[168:171], v[198:201], v[36:39]
	v_mfma_f32_16x16x32_bf16 v[32:35], v[176:179], v[198:201], v[32:35]
	v_mfma_f32_16x16x32_bf16 v[20:23], v[168:171], v[206:209], v[20:23]
	v_mfma_f32_16x16x32_bf16 v[16:19], v[176:179], v[206:209], v[16:19]
	v_mfma_f32_16x16x32_bf16 v[4:7], v[168:171], v[214:217], v[4:7]
	v_mfma_f32_16x16x32_bf16 v[0:3], v[176:179], v[214:217], v[0:3]
	s_setprio 0
	s_barrier
	s_add_i32 s77, 0, 0x18000
	s_add_i32 s81, 0, 0x1c000
	v_add_u32_e32 v154, s77, v165
	v_add_u32_e32 v176, s81, v165
	ds_read_b128 v[142:145], v154
	ds_read_b128 v[146:149], v154 offset:1024
	ds_read_b128 v[150:153], v154 offset:2048
	ds_read_b128 v[154:157], v154 offset:3072
	ds_read_b128 v[158:161], v176
	ds_read_b128 v[168:171], v176 offset:1024
	ds_read_b128 v[172:175], v176 offset:2048
	ds_read_b128 v[176:179], v176 offset:3072
	s_add_u32 s40, s40, s24
	s_addc_u32 s41, s41, 0
	s_mov_b32 m0, s49
	v_lshl_add_u64 v[242:243], s[40:41], 0, v[128:129]
	ds_read_b128 v[180:183], v167 offset:32768
	ds_read_b128 v[184:187], v167 offset:33792
	ds_read_b128 v[188:191], v167 offset:34816
	ds_read_b128 v[198:201], v167 offset:35840
	ds_read_b128 v[202:205], v167 offset:36864
	ds_read_b128 v[206:209], v167 offset:37888
	ds_read_b128 v[210:213], v167 offset:38912
	ds_read_b128 v[214:217], v167 offset:39936
	global_load_lds_dwordx4 v[242:243], off
	v_lshl_add_u64 v[242:243], s[40:41], 0, v[132:133]
	s_mov_b32 m0, s83
	s_nop 0
	global_load_lds_dwordx4 v[242:243], off
	s_waitcnt vmcnt(8)
	s_waitcnt lgkmcnt(0)
	s_barrier
	s_setprio 1
	s_waitcnt lgkmcnt(0)
	v_mfma_f32_16x16x32_bf16 v[124:127], v[142:145], v[180:183], v[124:127]
	v_mfma_f32_16x16x32_bf16 v[120:123], v[150:153], v[180:183], v[120:123]
	v_mfma_f32_16x16x32_bf16 v[108:111], v[142:145], v[188:191], v[108:111]
	v_mfma_f32_16x16x32_bf16 v[104:107], v[150:153], v[188:191], v[104:107]
	v_mfma_f32_16x16x32_bf16 v[92:95], v[142:145], v[202:205], v[92:95]
	v_mfma_f32_16x16x32_bf16 v[88:91], v[150:153], v[202:205], v[88:91]
	v_mfma_f32_16x16x32_bf16 v[76:79], v[142:145], v[210:213], v[76:79]
	v_mfma_f32_16x16x32_bf16 v[72:75], v[150:153], v[210:213], v[72:75]
	v_mfma_f32_16x16x32_bf16 v[124:127], v[146:149], v[184:187], v[124:127]
	v_mfma_f32_16x16x32_bf16 v[120:123], v[154:157], v[184:187], v[120:123]
	v_mfma_f32_16x16x32_bf16 v[108:111], v[146:149], v[198:201], v[108:111]
	v_mfma_f32_16x16x32_bf16 v[104:107], v[154:157], v[198:201], v[104:107]
	v_mfma_f32_16x16x32_bf16 v[92:95], v[146:149], v[206:209], v[92:95]
	v_mfma_f32_16x16x32_bf16 v[88:91], v[154:157], v[206:209], v[88:91]
	v_mfma_f32_16x16x32_bf16 v[76:79], v[146:149], v[214:217], v[76:79]
	v_mfma_f32_16x16x32_bf16 v[72:75], v[154:157], v[214:217], v[72:75]
	v_mfma_f32_16x16x32_bf16 v[116:119], v[158:161], v[180:183], v[116:119]
	v_mfma_f32_16x16x32_bf16 v[112:115], v[172:175], v[180:183], v[112:115]
	v_mfma_f32_16x16x32_bf16 v[100:103], v[158:161], v[188:191], v[100:103]
	v_mfma_f32_16x16x32_bf16 v[96:99], v[172:175], v[188:191], v[96:99]
	v_mfma_f32_16x16x32_bf16 v[84:87], v[158:161], v[202:205], v[84:87]
	v_mfma_f32_16x16x32_bf16 v[80:83], v[172:175], v[202:205], v[80:83]
	v_mfma_f32_16x16x32_bf16 v[68:71], v[158:161], v[210:213], v[68:71]
	v_mfma_f32_16x16x32_bf16 v[64:67], v[172:175], v[210:213], v[64:67]
	v_mfma_f32_16x16x32_bf16 v[116:119], v[168:171], v[184:187], v[116:119]
	v_mfma_f32_16x16x32_bf16 v[112:115], v[176:179], v[184:187], v[112:115]
	v_mfma_f32_16x16x32_bf16 v[100:103], v[168:171], v[198:201], v[100:103]
	v_mfma_f32_16x16x32_bf16 v[96:99], v[176:179], v[198:201], v[96:99]
	v_mfma_f32_16x16x32_bf16 v[84:87], v[168:171], v[206:209], v[84:87]
	v_mfma_f32_16x16x32_bf16 v[80:83], v[176:179], v[206:209], v[80:83]
	v_mfma_f32_16x16x32_bf16 v[68:71], v[168:171], v[214:217], v[68:71]
	v_mfma_f32_16x16x32_bf16 v[64:67], v[176:179], v[214:217], v[64:67]
	s_setprio 0
	s_barrier
; #define PG8_STAGE(bufoff, gbase, voff) do { _Pragma("unroll") for (int _i = 0; _i < 2; ++_i) \
;         __builtin_amdgcn_global_load_lds((const unsigned*)((const char*)(gbase) + (voff)[_i]), (PG8_LAS unsigned*)(lds + (bufoff) + ldsw + _i * 8192), 16, 0, 0); } while (0)
; #define PG8_WAIT_V(n) asm volatile("s_waitcnt vmcnt(" #n ")" ::: "memory")
; #define PG8_WAIT_L(n) asm volatile("s_waitcnt lgkmcnt(" #n ")" ::: "memory")
; template <class Epi, class Sched, bool ALIGN_EPI = false, bool SP2 = false>
; __device__ __forceinline__ void gemm_phase(PG8_LAS unsigned char* lds, const Gemm g, const Sched& S, const Epi& E) {
;     ...
;             PG8_LDA(At, 1, 1); PG8_STAGE(PG8_SB(1, 0), b3, voffB); PG8_STAGE(PG8_SB(1, 1), b3 + hstepB, voffB); PG8_STAGE(PG8_SA(1, 0), a3, voffA);
;             PG8_WAIT_V(8); PG8_WAIT_L(0); PG8_BAR; PG8_MMA(1, 0, At, B0); PG8_MMA(1, 1, At, B1); PG8_BAR; PG8_SCHED;
;             } else {
;             PG8_LDB(B0, 0, 0); PG8_SCHED; PG8_LDA(At, 0, 0); PG8_STAGE(PG8_SA(1, 1), a1 + hstepA, voffA);
;             PG8_WAIT_L(8); PG8_BAR; PG8_WAIT_L(0); PG8_MMA(0, 0, At, B0); PG8_BAR; PG8_SCHED;
;             PG8_LDB(B1, 0, 1); PG8_STAGE(PG8_SB(0, 0), b2, voffB);
;             PG8_BAR; PG8_WAIT_L(0); PG8_MMA(0, 1, At, B1); PG8_BAR;
;             PG8_LDA(At, 0, 1); PG8_STAGE(PG8_SA(0, 0), a2, voffA);
;             PG8_BAR; PG8_WAIT_L(0); PG8_MMA(1, 0, At, B0); PG8_BAR; PG8_SCHED;
;             PG8_STAGE(PG8_SB(0, 1), b2 + hstepB, voffB);
;             PG8_WAIT_V(6); PG8_BAR; PG8_MMA(1, 1, At, B1); PG8_BAR;
;             PG8_LDB(B0, 1, 0); PG8_SCHED; PG8_LDA(At, 1, 0); PG8_STAGE(PG8_SA(0, 1), a2 + hstepA, voffA);
;             PG8_WAIT_L(8); PG8_BAR; PG8_WAIT_L(0); PG8_MMA(0, 0, At, B0); PG8_BAR; PG8_SCHED;
;             PG8_LDB(B1, 1, 1); PG8_STAGE(PG8_SB(1, 0), b3, voffB);
;             PG8_BAR; PG8_WAIT_L(0); PG8_MMA(0, 1, At, B1); PG8_BAR;
;             PG8_LDA(At, 1, 1); PG8_STAGE(PG8_SA(1, 0), a3, voffA);
;             PG8_BAR; PG8_WAIT_L(0); PG8_MMA(1, 0, At, B0); PG8_BAR; PG8_SCHED;
;             PG8_STAGE(PG8_SB(1, 1), b3 + hstepB, voffB);
;             PG8_WAIT_V(6); PG8_BAR; PG8_MMA(1, 1, At, B1); PG8_BAR;
;             }
;         }
;         if constexpr (ALIGN_EPI) { if (wr == 0) PG8_BAR; }
;         if constexpr (!Epi::AFTER_DRAIN) { E(acc, cur, wr, wc, fr, fq); S.done(cur); }
;         if (!has_next) break;
	s_add_i32 s40, s77, s56
	v_lshl_add_u64 v[162:163], v[162:163], 0, s[28:29]
	s_mov_b32 m0, s40
	ds_read_b128 v[180:183], v167 offset:49152
	ds_read_b128 v[184:187], v167 offset:50176
	ds_read_b128 v[188:191], v167 offset:51200
	ds_read_b128 v[198:201], v167 offset:52224
	ds_read_b128 v[202:205], v167 offset:53248
	ds_read_b128 v[206:209], v167 offset:54272
	ds_read_b128 v[210:213], v167 offset:55296
	ds_read_b128 v[214:217], v167 offset:56320
	global_load_lds_dwordx4 v[162:163], off
	v_lshl_add_u64 v[162:163], v[218:219], 0, s[28:29]
	s_add_i32 m0, s40, 0x2000
	s_add_i32 s40, s81, s56
	global_load_lds_dwordx4 v[162:163], off
	v_lshl_add_u64 v[162:163], v[220:221], 0, s[28:29]
	s_mov_b32 m0, s40
	s_nop 0
	global_load_lds_dwordx4 v[162:163], off
	v_lshl_add_u64 v[162:163], v[222:223], 0, s[28:29]
	s_add_i32 m0, s40, 0x2000
	s_nop 0
	global_load_lds_dwordx4 v[162:163], off
	v_lshl_add_u64 v[162:163], v[224:225], 0, s[28:29]
	s_mov_b32 m0, s36
	s_nop 0
	global_load_lds_dwordx4 v[162:163], off
	v_lshl_add_u64 v[162:163], v[250:251], 0, s[28:29]
	s_mov_b32 m0, s37
	s_nop 0
	global_load_lds_dwordx4 v[162:163], off
	s_waitcnt vmcnt(8)
	s_waitcnt lgkmcnt(0)
	s_barrier
	s_setprio 1
	s_waitcnt lgkmcnt(0)
	v_mfma_f32_16x16x32_bf16 v[60:63], v[142:145], v[180:183], v[60:63]
	v_mfma_f32_16x16x32_bf16 v[56:59], v[150:153], v[180:183], v[56:59]
	v_mfma_f32_16x16x32_bf16 v[44:47], v[142:145], v[188:191], v[44:47]
	v_mfma_f32_16x16x32_bf16 v[40:43], v[150:153], v[188:191], v[40:43]
	v_mfma_f32_16x16x32_bf16 v[28:31], v[142:145], v[202:205], v[28:31]
	v_mfma_f32_16x16x32_bf16 v[24:27], v[150:153], v[202:205], v[24:27]
	v_mfma_f32_16x16x32_bf16 v[12:15], v[142:145], v[210:213], v[12:15]
	v_mfma_f32_16x16x32_bf16 v[8:11], v[150:153], v[210:213], v[8:11]
	v_mfma_f32_16x16x32_bf16 v[60:63], v[146:149], v[184:187], v[60:63]
	v_mfma_f32_16x16x32_bf16 v[56:59], v[154:157], v[184:187], v[56:59]
	v_mfma_f32_16x16x32_bf16 v[44:47], v[146:149], v[198:201], v[44:47]
	v_mfma_f32_16x16x32_bf16 v[40:43], v[154:157], v[198:201], v[40:43]
	v_mfma_f32_16x16x32_bf16 v[28:31], v[146:149], v[206:209], v[28:31]
	v_mfma_f32_16x16x32_bf16 v[24:27], v[154:157], v[206:209], v[24:27]
	v_mfma_f32_16x16x32_bf16 v[12:15], v[146:149], v[214:217], v[12:15]
	v_mfma_f32_16x16x32_bf16 v[8:11], v[154:157], v[214:217], v[8:11]
	v_mfma_f32_16x16x32_bf16 v[52:55], v[158:161], v[180:183], v[52:55]
	v_mfma_f32_16x16x32_bf16 v[48:51], v[172:175], v[180:183], v[48:51]
	v_mfma_f32_16x16x32_bf16 v[36:39], v[158:161], v[188:191], v[36:39]
	v_mfma_f32_16x16x32_bf16 v[32:35], v[172:175], v[188:191], v[32:35]
	v_mfma_f32_16x16x32_bf16 v[20:23], v[158:161], v[202:205], v[20:23]
	v_mfma_f32_16x16x32_bf16 v[16:19], v[172:175], v[202:205], v[16:19]
	v_mfma_f32_16x16x32_bf16 v[4:7], v[158:161], v[210:213], v[4:7]
	v_mfma_f32_16x16x32_bf16 v[0:3], v[172:175], v[210:213], v[0:3]
	v_mfma_f32_16x16x32_bf16 v[52:55], v[168:171], v[184:187], v[52:55]
	v_mfma_f32_16x16x32_bf16 v[48:51], v[176:179], v[184:187], v[48:51]
	v_mfma_f32_16x16x32_bf16 v[36:39], v[168:171], v[198:201], v[36:39]
	v_mfma_f32_16x16x32_bf16 v[32:35], v[176:179], v[198:201], v[32:35]
	v_mfma_f32_16x16x32_bf16 v[20:23], v[168:171], v[206:209], v[20:23]
	v_mfma_f32_16x16x32_bf16 v[16:19], v[176:179], v[206:209], v[16:19]
	v_mfma_f32_16x16x32_bf16 v[4:7], v[168:171], v[214:217], v[4:7]
	v_mfma_f32_16x16x32_bf16 v[0:3], v[176:179], v[214:217], v[0:3]
	s_setprio 0
	s_barrier
	s_add_u32 vcc_lo, vcc_lo, 0x100
	s_addc_u32 vcc_hi, vcc_hi, 0
	s_add_u32 s44, s44, 0x100
	s_addc_u32 s45, s45, 0
	s_cmp_ge_u32 s76, s51
	s_mov_b32 s40, s76
	s_cbranch_scc0 .LBB0_460
	s_and_b64 vcc, exec, s[74:75]
	s_cbranch_vccz .LBB0_463
	s_barrier
